# silu-gate tile epilogue stores (SG) write-through (sc1): less dirty L2 to flush at the in-proj->attention barriers
# speedup vs baseline: 1.0107x; 1.0048x over previous
.LBB0_972:
	s_and_b64 vcc, exec, s[4:5]
	s_cbranch_vccz .LBB0_974
	s_and_b64 s[4:5], s[22:23], exec
	s_mov_b64 s[4:5], s[0:1]
	s_cselect_b32 s6, -3, -6
	s_load_dwordx2 s[4:5], s[4:5], 0xd0
	s_add_i32 s6, s6, s74
	s_lshl_b32 s6, s6, 8
	s_ashr_i32 s7, s6, 31
	s_lshl_b64 s[6:7], s[6:7], 1
	s_waitcnt lgkmcnt(0)
	s_add_u32 s4, s4, s6
	v_lshlrev_b32_e32 v130, 3, v191
	s_addc_u32 s5, s5, s7
	v_ashrrev_i32_e32 v131, 31, v130
	v_readlane_b32 s6, v254, 45
	v_lshl_add_u64 v[130:131], v[130:131], 1, s[4:5]
	s_mov_b64 s[4:5], 0x6000000
	v_or_b32_e32 v112, s6, v189
	v_lshl_add_u64 v[130:131], v[130:131], 0, s[4:5]
	v_readlane_b32 s4, v254, 36
	s_cmp_eq_u32 s39, 3
	v_readlane_b32 s5, v254, 37
	v_lshl_add_u32 v132, s4, 8, v112
	v_ashrrev_i32_e32 v133, 31, v132
	v_mul_f32_e32 v112, 0xbfb8aa3b, v126
	v_lshlrev_b64 v[134:135], 11, v[132:133]
	v_exp_f32_e32 v112, v112
	v_mul_f32_e32 v133, 0xbfb8aa3b, v127
	v_exp_f32_e32 v133, v133
	v_lshl_add_u64 v[138:139], v[130:131], 0, v[134:135]
	v_add_f32_e32 v112, 1.0, v112
	v_rcp_f32_e32 v134, v112
	v_add_f32_e32 v112, 1.0, v133
	v_mul_f32_e32 v133, 0xbfb8aa3b, v128
	v_exp_f32_e32 v133, v133
	v_mul_f32_e32 v135, 0xbfb8aa3b, v129
	v_exp_f32_e32 v137, v135
	v_rcp_f32_e32 v135, v112
	v_add_f32_e32 v112, 1.0, v133
	v_mul_f32_e32 v133, 0xbfb8aa3b, v122
	v_rcp_f32_e32 v136, v112
	v_add_f32_e32 v112, 1.0, v137
	v_exp_f32_e32 v133, v133
	v_mul_f32_e32 v137, 0xbfb8aa3b, v123
	v_exp_f32_e32 v141, v137
	v_rcp_f32_e32 v137, v112
	v_add_f32_e32 v112, 1.0, v133
	v_mul_f32_e32 v133, 0xbfb8aa3b, v124
	v_rcp_f32_e32 v140, v112
	v_add_f32_e32 v112, 1.0, v141
	v_exp_f32_e32 v133, v133
	v_mul_f32_e32 v141, 0xbfb8aa3b, v125
	v_exp_f32_e32 v143, v141
	v_rcp_f32_e32 v141, v112
	v_add_f32_e32 v112, 1.0, v133
	v_rcp_f32_e32 v142, v112
	v_add_f32_e32 v112, 1.0, v143
	v_rcp_f32_e32 v143, v112
	v_mul_f32_e32 v112, 0xbfb8aa3b, v118
	v_exp_f32_e32 v112, v112
	v_mul_f32_e32 v133, 0xbfb8aa3b, v119
	v_readlane_b32 s4, v255, 29
	v_exp_f32_e32 v133, v133
	s_cselect_b32 s4, s19, s4
	v_readlane_b32 s5, v255, 28
	v_readlane_b32 s6, v255, 30
	v_pk_mul_f32 v[134:135], v[126:127], v[134:135]
	v_pk_mul_f32 v[136:137], v[128:129], v[136:137]
	v_pk_mul_f32 v[140:141], v[122:123], v[140:141]
	v_pk_mul_f32 v[142:143], v[124:125], v[142:143]
	s_cselect_b32 s6, s5, s6
	s_lshl_b32 s4, s4, 1
	s_mov_b32 s5, s15
	v_cvt_pk_bf16_f32 v134, v134, v135
	v_cvt_pk_bf16_f32 v135, v136, v137
	v_cvt_pk_bf16_f32 v136, v140, v141
	v_cvt_pk_bf16_f32 v137, v142, v143
	v_lshl_add_u64 v[140:141], v[138:139], 0, s[4:5]
	v_add_f32_e32 v112, 1.0, v112
	global_store_dwordx4 v[140:141], v[134:137], off sc1
	s_lshl_b32 s6, s6, 1
	s_mov_b32 s7, s15
	v_rcp_f32_e32 v134, v112
	v_add_f32_e32 v112, 1.0, v133
	v_mul_f32_e32 v133, 0xbfb8aa3b, v120
	v_exp_f32_e32 v133, v133
	v_mul_f32_e32 v135, 0xbfb8aa3b, v121
	v_exp_f32_e32 v137, v135
	v_rcp_f32_e32 v135, v112
	v_add_f32_e32 v112, 1.0, v133
	v_mul_f32_e32 v133, 0xbfb8aa3b, v114
	v_rcp_f32_e32 v136, v112
	v_add_f32_e32 v112, 1.0, v137
	v_exp_f32_e32 v133, v133
	v_mul_f32_e32 v137, 0xbfb8aa3b, v115
	v_exp_f32_e32 v141, v137
	v_rcp_f32_e32 v137, v112
	v_add_f32_e32 v112, 1.0, v133
	v_mul_f32_e32 v133, 0xbfb8aa3b, v116
	v_rcp_f32_e32 v140, v112
	v_add_f32_e32 v112, 1.0, v141
	v_exp_f32_e32 v133, v133
	v_mul_f32_e32 v141, 0xbfb8aa3b, v117
	v_exp_f32_e32 v143, v141
	v_rcp_f32_e32 v141, v112
	v_add_f32_e32 v112, 1.0, v133
	v_rcp_f32_e32 v142, v112
	v_add_f32_e32 v112, 1.0, v143
	v_rcp_f32_e32 v143, v112
	v_mul_f32_e32 v112, 0xbfb8aa3b, v108
	v_pk_mul_f32 v[134:135], v[118:119], v[134:135]
	v_pk_mul_f32 v[136:137], v[120:121], v[136:137]
	v_pk_mul_f32 v[140:141], v[114:115], v[140:141]
	v_pk_mul_f32 v[142:143], v[116:117], v[142:143]
	v_exp_f32_e32 v112, v112
	v_mul_f32_e32 v133, 0xbfb8aa3b, v109
	v_cvt_pk_bf16_f32 v134, v134, v135
	v_cvt_pk_bf16_f32 v135, v136, v137
	v_cvt_pk_bf16_f32 v136, v140, v141
	v_cvt_pk_bf16_f32 v137, v142, v143
	v_lshl_add_u64 v[138:139], v[138:139], 0, s[6:7]
	v_exp_f32_e32 v133, v133
	global_store_dwordx4 v[138:139], v[134:137], off sc1
	v_add_f32_e32 v112, 1.0, v112
	s_nop 0
	v_or_b32_e32 v134, 16, v132
	v_ashrrev_i32_e32 v135, 31, v134
	v_lshlrev_b64 v[134:135], 11, v[134:135]
	v_lshl_add_u64 v[138:139], v[130:131], 0, v[134:135]
	v_rcp_f32_e32 v134, v112
	v_add_f32_e32 v112, 1.0, v133
	v_mul_f32_e32 v133, 0xbfb8aa3b, v110
	v_exp_f32_e32 v133, v133
	v_mul_f32_e32 v135, 0xbfb8aa3b, v111
	v_exp_f32_e32 v137, v135
	v_rcp_f32_e32 v135, v112
	v_add_f32_e32 v112, 1.0, v133
	v_mul_f32_e32 v133, 0xbfb8aa3b, v104
	v_rcp_f32_e32 v136, v112
	v_add_f32_e32 v112, 1.0, v137
	v_exp_f32_e32 v133, v133
	v_mul_f32_e32 v137, 0xbfb8aa3b, v105
	v_exp_f32_e32 v141, v137
	v_rcp_f32_e32 v137, v112
	v_add_f32_e32 v112, 1.0, v133
	v_mul_f32_e32 v133, 0xbfb8aa3b, v106
	v_rcp_f32_e32 v140, v112
	v_add_f32_e32 v112, 1.0, v141
	v_exp_f32_e32 v133, v133
	v_mul_f32_e32 v141, 0xbfb8aa3b, v107
	v_exp_f32_e32 v143, v141
	v_rcp_f32_e32 v141, v112
	v_add_f32_e32 v112, 1.0, v133
	v_rcp_f32_e32 v142, v112
	v_add_f32_e32 v112, 1.0, v143
	v_rcp_f32_e32 v143, v112
	v_mul_f32_e32 v112, 0xbfb8aa3b, v100
	v_exp_f32_e32 v112, v112
	v_mul_f32_e32 v133, 0xbfb8aa3b, v101
	v_exp_f32_e32 v133, v133
	v_pk_mul_f32 v[134:135], v[108:109], v[134:135]
	v_pk_mul_f32 v[136:137], v[110:111], v[136:137]
	v_pk_mul_f32 v[140:141], v[104:105], v[140:141]
	v_pk_mul_f32 v[142:143], v[106:107], v[142:143]
	v_cvt_pk_bf16_f32 v134, v134, v135
	v_cvt_pk_bf16_f32 v135, v136, v137
	v_cvt_pk_bf16_f32 v136, v140, v141
	v_cvt_pk_bf16_f32 v137, v142, v143
	v_lshl_add_u64 v[140:141], v[138:139], 0, s[4:5]
	v_add_f32_e32 v112, 1.0, v112
	global_store_dwordx4 v[140:141], v[134:137], off sc1
	v_lshl_add_u64 v[138:139], v[138:139], 0, s[6:7]
	s_nop 0
	v_rcp_f32_e32 v134, v112
	v_add_f32_e32 v112, 1.0, v133
	v_mul_f32_e32 v133, 0xbfb8aa3b, v102
	v_exp_f32_e32 v133, v133
	v_mul_f32_e32 v135, 0xbfb8aa3b, v103
	v_exp_f32_e32 v137, v135
	v_rcp_f32_e32 v135, v112
	v_add_f32_e32 v112, 1.0, v133
	v_mul_f32_e32 v133, 0xbfb8aa3b, v96
	v_rcp_f32_e32 v136, v112
	v_add_f32_e32 v112, 1.0, v137
	v_exp_f32_e32 v133, v133
	v_mul_f32_e32 v137, 0xbfb8aa3b, v97
	v_exp_f32_e32 v141, v137
	v_rcp_f32_e32 v137, v112
	v_add_f32_e32 v112, 1.0, v133
	v_mul_f32_e32 v133, 0xbfb8aa3b, v98
	v_rcp_f32_e32 v140, v112
	v_add_f32_e32 v112, 1.0, v141
	v_exp_f32_e32 v133, v133
	v_mul_f32_e32 v141, 0xbfb8aa3b, v99
	v_exp_f32_e32 v143, v141
	v_rcp_f32_e32 v141, v112
	v_add_f32_e32 v112, 1.0, v133
	v_rcp_f32_e32 v142, v112
	v_add_f32_e32 v112, 1.0, v143
	v_rcp_f32_e32 v143, v112
	v_mul_f32_e32 v112, 0xbfb8aa3b, v92
	v_pk_mul_f32 v[134:135], v[100:101], v[134:135]
	v_pk_mul_f32 v[136:137], v[102:103], v[136:137]
	v_pk_mul_f32 v[140:141], v[96:97], v[140:141]
	v_pk_mul_f32 v[142:143], v[98:99], v[142:143]
	v_exp_f32_e32 v112, v112
	v_mul_f32_e32 v133, 0xbfb8aa3b, v93
	v_cvt_pk_bf16_f32 v134, v134, v135
	v_cvt_pk_bf16_f32 v135, v136, v137
	v_cvt_pk_bf16_f32 v136, v140, v141
	v_cvt_pk_bf16_f32 v137, v142, v143
	v_exp_f32_e32 v133, v133
	global_store_dwordx4 v[138:139], v[134:137], off sc1
	v_add_f32_e32 v112, 1.0, v112
	s_nop 0
	v_or_b32_e32 v134, 32, v132
	v_ashrrev_i32_e32 v135, 31, v134
	v_lshlrev_b64 v[134:135], 11, v[134:135]
	v_lshl_add_u64 v[138:139], v[130:131], 0, v[134:135]
	v_rcp_f32_e32 v134, v112
	v_add_f32_e32 v112, 1.0, v133
	v_mul_f32_e32 v133, 0xbfb8aa3b, v94
	v_exp_f32_e32 v133, v133
	v_mul_f32_e32 v135, 0xbfb8aa3b, v95
	v_exp_f32_e32 v137, v135
	v_rcp_f32_e32 v135, v112
	v_add_f32_e32 v112, 1.0, v133
	v_mul_f32_e32 v133, 0xbfb8aa3b, v88
	v_rcp_f32_e32 v136, v112
	v_add_f32_e32 v112, 1.0, v137
	v_exp_f32_e32 v133, v133
	v_mul_f32_e32 v137, 0xbfb8aa3b, v89
	v_exp_f32_e32 v141, v137
	v_rcp_f32_e32 v137, v112
	v_add_f32_e32 v112, 1.0, v133
	v_mul_f32_e32 v133, 0xbfb8aa3b, v90
	v_rcp_f32_e32 v140, v112
	v_add_f32_e32 v112, 1.0, v141
	v_exp_f32_e32 v133, v133
	v_mul_f32_e32 v141, 0xbfb8aa3b, v91
	v_exp_f32_e32 v143, v141
	v_rcp_f32_e32 v141, v112
	v_add_f32_e32 v112, 1.0, v133
	v_rcp_f32_e32 v142, v112
	v_add_f32_e32 v112, 1.0, v143
	v_rcp_f32_e32 v143, v112
	v_mul_f32_e32 v112, 0xbfb8aa3b, v84
	v_exp_f32_e32 v112, v112
	v_mul_f32_e32 v133, 0xbfb8aa3b, v85
	v_exp_f32_e32 v133, v133
	v_pk_mul_f32 v[134:135], v[92:93], v[134:135]
	v_pk_mul_f32 v[136:137], v[94:95], v[136:137]
	v_pk_mul_f32 v[140:141], v[88:89], v[140:141]
	v_pk_mul_f32 v[142:143], v[90:91], v[142:143]
	v_cvt_pk_bf16_f32 v134, v134, v135
	v_cvt_pk_bf16_f32 v135, v136, v137
	v_cvt_pk_bf16_f32 v136, v140, v141
	v_cvt_pk_bf16_f32 v137, v142, v143
	v_lshl_add_u64 v[140:141], v[138:139], 0, s[4:5]
	v_add_f32_e32 v112, 1.0, v112
	global_store_dwordx4 v[140:141], v[134:137], off sc1
	v_lshl_add_u64 v[138:139], v[138:139], 0, s[6:7]
	s_nop 0
	v_rcp_f32_e32 v134, v112
	v_add_f32_e32 v112, 1.0, v133
	v_mul_f32_e32 v133, 0xbfb8aa3b, v86
	v_exp_f32_e32 v133, v133
	v_mul_f32_e32 v135, 0xbfb8aa3b, v87
	v_exp_f32_e32 v137, v135
	v_rcp_f32_e32 v135, v112
	v_add_f32_e32 v112, 1.0, v133
	v_mul_f32_e32 v133, 0xbfb8aa3b, v80
	v_rcp_f32_e32 v136, v112
	v_add_f32_e32 v112, 1.0, v137
	v_exp_f32_e32 v133, v133
	v_mul_f32_e32 v137, 0xbfb8aa3b, v81
	v_exp_f32_e32 v141, v137
	v_rcp_f32_e32 v137, v112
	v_add_f32_e32 v112, 1.0, v133
	v_mul_f32_e32 v133, 0xbfb8aa3b, v82
	v_rcp_f32_e32 v140, v112
	v_add_f32_e32 v112, 1.0, v141
	v_exp_f32_e32 v133, v133
	v_mul_f32_e32 v141, 0xbfb8aa3b, v83
	v_exp_f32_e32 v143, v141
	v_rcp_f32_e32 v141, v112
	v_add_f32_e32 v112, 1.0, v133
	v_rcp_f32_e32 v142, v112
	v_add_f32_e32 v112, 1.0, v143
	v_rcp_f32_e32 v143, v112
	v_mul_f32_e32 v112, 0xbfb8aa3b, v76
	v_pk_mul_f32 v[134:135], v[84:85], v[134:135]
	v_pk_mul_f32 v[136:137], v[86:87], v[136:137]
	v_pk_mul_f32 v[140:141], v[80:81], v[140:141]
	v_pk_mul_f32 v[142:143], v[82:83], v[142:143]
	v_exp_f32_e32 v112, v112
	v_mul_f32_e32 v133, 0xbfb8aa3b, v77
	v_cvt_pk_bf16_f32 v134, v134, v135
	v_cvt_pk_bf16_f32 v135, v136, v137
	v_cvt_pk_bf16_f32 v136, v140, v141
	v_cvt_pk_bf16_f32 v137, v142, v143
	v_exp_f32_e32 v133, v133
	global_store_dwordx4 v[138:139], v[134:137], off sc1
	v_add_f32_e32 v112, 1.0, v112
	s_nop 0
	v_or_b32_e32 v134, 48, v132
	v_ashrrev_i32_e32 v135, 31, v134
	v_lshlrev_b64 v[134:135], 11, v[134:135]
	v_lshl_add_u64 v[138:139], v[130:131], 0, v[134:135]
	v_rcp_f32_e32 v134, v112
	v_add_f32_e32 v112, 1.0, v133
	v_mul_f32_e32 v133, 0xbfb8aa3b, v78
	v_exp_f32_e32 v133, v133
	v_mul_f32_e32 v135, 0xbfb8aa3b, v79
	v_exp_f32_e32 v137, v135
	v_rcp_f32_e32 v135, v112
	v_add_f32_e32 v112, 1.0, v133
	v_mul_f32_e32 v133, 0xbfb8aa3b, v72
	v_rcp_f32_e32 v136, v112
	v_add_f32_e32 v112, 1.0, v137
	v_exp_f32_e32 v133, v133
	v_mul_f32_e32 v137, 0xbfb8aa3b, v73
	v_exp_f32_e32 v141, v137
	v_rcp_f32_e32 v137, v112
	v_add_f32_e32 v112, 1.0, v133
	v_mul_f32_e32 v133, 0xbfb8aa3b, v74
	v_rcp_f32_e32 v140, v112
	v_add_f32_e32 v112, 1.0, v141
	v_exp_f32_e32 v133, v133
	v_mul_f32_e32 v141, 0xbfb8aa3b, v75
	v_exp_f32_e32 v143, v141
	v_rcp_f32_e32 v141, v112
	v_add_f32_e32 v112, 1.0, v133
	v_rcp_f32_e32 v142, v112
	v_add_f32_e32 v112, 1.0, v143
	v_rcp_f32_e32 v143, v112
	v_mul_f32_e32 v112, 0xbfb8aa3b, v68
	v_exp_f32_e32 v112, v112
	v_mul_f32_e32 v133, 0xbfb8aa3b, v69
	v_exp_f32_e32 v133, v133
	v_pk_mul_f32 v[134:135], v[76:77], v[134:135]
	v_pk_mul_f32 v[136:137], v[78:79], v[136:137]
	v_pk_mul_f32 v[140:141], v[72:73], v[140:141]
	v_pk_mul_f32 v[142:143], v[74:75], v[142:143]
	v_cvt_pk_bf16_f32 v134, v134, v135
	v_cvt_pk_bf16_f32 v135, v136, v137
	v_cvt_pk_bf16_f32 v136, v140, v141
	v_cvt_pk_bf16_f32 v137, v142, v143
	v_lshl_add_u64 v[140:141], v[138:139], 0, s[4:5]
	v_add_f32_e32 v112, 1.0, v112
	global_store_dwordx4 v[140:141], v[134:137], off sc1
	v_lshl_add_u64 v[138:139], v[138:139], 0, s[6:7]
	s_nop 0
	v_rcp_f32_e32 v134, v112
	v_add_f32_e32 v112, 1.0, v133
	v_mul_f32_e32 v133, 0xbfb8aa3b, v70
	v_exp_f32_e32 v133, v133
	v_mul_f32_e32 v135, 0xbfb8aa3b, v71
	v_exp_f32_e32 v137, v135
	v_rcp_f32_e32 v135, v112
	v_add_f32_e32 v112, 1.0, v133
	v_mul_f32_e32 v133, 0xbfb8aa3b, v64
	v_rcp_f32_e32 v136, v112
	v_add_f32_e32 v112, 1.0, v137
	v_exp_f32_e32 v133, v133
	v_mul_f32_e32 v137, 0xbfb8aa3b, v65
	v_exp_f32_e32 v141, v137
	v_rcp_f32_e32 v137, v112
	v_add_f32_e32 v112, 1.0, v133
	v_mul_f32_e32 v133, 0xbfb8aa3b, v66
	v_rcp_f32_e32 v140, v112
	v_add_f32_e32 v112, 1.0, v141
	v_exp_f32_e32 v133, v133
	v_mul_f32_e32 v141, 0xbfb8aa3b, v67
	v_exp_f32_e32 v143, v141
	v_rcp_f32_e32 v141, v112
	v_add_f32_e32 v112, 1.0, v133
	v_rcp_f32_e32 v142, v112
	v_add_f32_e32 v112, 1.0, v143
	v_rcp_f32_e32 v143, v112
	v_mul_f32_e32 v112, 0xbfb8aa3b, v60
	v_pk_mul_f32 v[134:135], v[68:69], v[134:135]
	v_pk_mul_f32 v[136:137], v[70:71], v[136:137]
	v_pk_mul_f32 v[140:141], v[64:65], v[140:141]
	v_pk_mul_f32 v[142:143], v[66:67], v[142:143]
	v_exp_f32_e32 v112, v112
	v_mul_f32_e32 v133, 0xbfb8aa3b, v61
	v_cvt_pk_bf16_f32 v134, v134, v135
	v_cvt_pk_bf16_f32 v135, v136, v137
	v_cvt_pk_bf16_f32 v136, v140, v141
	v_cvt_pk_bf16_f32 v137, v142, v143
	v_exp_f32_e32 v133, v133
	global_store_dwordx4 v[138:139], v[134:137], off sc1
	v_add_f32_e32 v112, 1.0, v112
	s_nop 0
	v_add_u32_e32 v134, 0x80, v132
	v_ashrrev_i32_e32 v135, 31, v134
	v_lshlrev_b64 v[134:135], 11, v[134:135]
	v_lshl_add_u64 v[138:139], v[130:131], 0, v[134:135]
	v_rcp_f32_e32 v134, v112
	v_add_f32_e32 v112, 1.0, v133
	v_mul_f32_e32 v133, 0xbfb8aa3b, v62
	v_exp_f32_e32 v133, v133
	v_mul_f32_e32 v135, 0xbfb8aa3b, v63
	v_exp_f32_e32 v137, v135
	v_rcp_f32_e32 v135, v112
	v_add_f32_e32 v112, 1.0, v133
	v_mul_f32_e32 v133, 0xbfb8aa3b, v56
	v_rcp_f32_e32 v136, v112
	v_add_f32_e32 v112, 1.0, v137
	v_exp_f32_e32 v133, v133
	v_mul_f32_e32 v137, 0xbfb8aa3b, v57
	v_exp_f32_e32 v141, v137
	v_rcp_f32_e32 v137, v112
	v_add_f32_e32 v112, 1.0, v133
	v_mul_f32_e32 v133, 0xbfb8aa3b, v58
	v_rcp_f32_e32 v140, v112
	v_add_f32_e32 v112, 1.0, v141
	v_exp_f32_e32 v133, v133
	v_mul_f32_e32 v141, 0xbfb8aa3b, v59
	v_exp_f32_e32 v143, v141
	v_rcp_f32_e32 v141, v112
	v_add_f32_e32 v112, 1.0, v133
	v_rcp_f32_e32 v142, v112
	v_add_f32_e32 v112, 1.0, v143
	v_rcp_f32_e32 v143, v112
	v_mul_f32_e32 v112, 0xbfb8aa3b, v52
	v_exp_f32_e32 v112, v112
	v_mul_f32_e32 v133, 0xbfb8aa3b, v53
	v_exp_f32_e32 v133, v133
	v_pk_mul_f32 v[134:135], v[60:61], v[134:135]
	v_pk_mul_f32 v[136:137], v[62:63], v[136:137]
	v_pk_mul_f32 v[140:141], v[56:57], v[140:141]
	v_pk_mul_f32 v[142:143], v[58:59], v[142:143]
	v_cvt_pk_bf16_f32 v134, v134, v135
	v_cvt_pk_bf16_f32 v135, v136, v137
	v_cvt_pk_bf16_f32 v136, v140, v141
	v_cvt_pk_bf16_f32 v137, v142, v143
	v_lshl_add_u64 v[140:141], v[138:139], 0, s[4:5]
	v_add_f32_e32 v112, 1.0, v112
	global_store_dwordx4 v[140:141], v[134:137], off sc1
	v_lshl_add_u64 v[138:139], v[138:139], 0, s[6:7]
	s_nop 0
	v_rcp_f32_e32 v134, v112
	v_add_f32_e32 v112, 1.0, v133
	v_mul_f32_e32 v133, 0xbfb8aa3b, v54
	v_exp_f32_e32 v133, v133
	v_mul_f32_e32 v135, 0xbfb8aa3b, v55
	v_exp_f32_e32 v137, v135
	v_rcp_f32_e32 v135, v112
	v_add_f32_e32 v112, 1.0, v133
	v_mul_f32_e32 v133, 0xbfb8aa3b, v48
	v_rcp_f32_e32 v136, v112
	v_add_f32_e32 v112, 1.0, v137
	v_exp_f32_e32 v133, v133
	v_mul_f32_e32 v137, 0xbfb8aa3b, v49
	v_exp_f32_e32 v141, v137
	v_rcp_f32_e32 v137, v112
	v_add_f32_e32 v112, 1.0, v133
	v_mul_f32_e32 v133, 0xbfb8aa3b, v50
	v_rcp_f32_e32 v140, v112
	v_add_f32_e32 v112, 1.0, v141
	v_exp_f32_e32 v133, v133
	v_mul_f32_e32 v141, 0xbfb8aa3b, v51
	v_exp_f32_e32 v143, v141
	v_rcp_f32_e32 v141, v112
	v_add_f32_e32 v112, 1.0, v133
	v_rcp_f32_e32 v142, v112
	v_add_f32_e32 v112, 1.0, v143
	v_rcp_f32_e32 v143, v112
	v_mul_f32_e32 v112, 0xbfb8aa3b, v44
	v_pk_mul_f32 v[134:135], v[52:53], v[134:135]
	v_pk_mul_f32 v[136:137], v[54:55], v[136:137]
	v_pk_mul_f32 v[140:141], v[48:49], v[140:141]
	v_pk_mul_f32 v[142:143], v[50:51], v[142:143]
	v_exp_f32_e32 v112, v112
	v_mul_f32_e32 v133, 0xbfb8aa3b, v45
	v_cvt_pk_bf16_f32 v134, v134, v135
	v_cvt_pk_bf16_f32 v135, v136, v137
	v_cvt_pk_bf16_f32 v136, v140, v141
	v_cvt_pk_bf16_f32 v137, v142, v143
	v_exp_f32_e32 v133, v133
	global_store_dwordx4 v[138:139], v[134:137], off sc1
	v_add_f32_e32 v112, 1.0, v112
	s_nop 0
	v_add_u32_e32 v134, 0x90, v132
	v_ashrrev_i32_e32 v135, 31, v134
	v_lshlrev_b64 v[134:135], 11, v[134:135]
	v_lshl_add_u64 v[138:139], v[130:131], 0, v[134:135]
	v_rcp_f32_e32 v134, v112
	v_add_f32_e32 v112, 1.0, v133
	v_mul_f32_e32 v133, 0xbfb8aa3b, v46
	v_exp_f32_e32 v133, v133
	v_mul_f32_e32 v135, 0xbfb8aa3b, v47
	v_exp_f32_e32 v137, v135
	v_rcp_f32_e32 v135, v112
	v_add_f32_e32 v112, 1.0, v133
	v_mul_f32_e32 v133, 0xbfb8aa3b, v40
	v_rcp_f32_e32 v136, v112
	v_add_f32_e32 v112, 1.0, v137
	v_exp_f32_e32 v133, v133
	v_mul_f32_e32 v137, 0xbfb8aa3b, v41
	v_exp_f32_e32 v141, v137
	v_rcp_f32_e32 v137, v112
	v_add_f32_e32 v112, 1.0, v133
	v_mul_f32_e32 v133, 0xbfb8aa3b, v42
	v_rcp_f32_e32 v140, v112
	v_add_f32_e32 v112, 1.0, v141
	v_exp_f32_e32 v133, v133
	v_mul_f32_e32 v141, 0xbfb8aa3b, v43
	v_exp_f32_e32 v143, v141
	v_rcp_f32_e32 v141, v112
	v_add_f32_e32 v112, 1.0, v133
	v_rcp_f32_e32 v142, v112
	v_add_f32_e32 v112, 1.0, v143
	v_rcp_f32_e32 v143, v112
	v_mul_f32_e32 v112, 0xbfb8aa3b, v36
	v_exp_f32_e32 v112, v112
	v_mul_f32_e32 v133, 0xbfb8aa3b, v37
	v_exp_f32_e32 v133, v133
	v_pk_mul_f32 v[134:135], v[44:45], v[134:135]
	v_pk_mul_f32 v[136:137], v[46:47], v[136:137]
	v_pk_mul_f32 v[140:141], v[40:41], v[140:141]
	v_pk_mul_f32 v[142:143], v[42:43], v[142:143]
	v_cvt_pk_bf16_f32 v134, v134, v135
	v_cvt_pk_bf16_f32 v135, v136, v137
	v_cvt_pk_bf16_f32 v136, v140, v141
	v_cvt_pk_bf16_f32 v137, v142, v143
	v_lshl_add_u64 v[140:141], v[138:139], 0, s[4:5]
	v_add_f32_e32 v112, 1.0, v112
	global_store_dwordx4 v[140:141], v[134:137], off sc1
	v_lshl_add_u64 v[138:139], v[138:139], 0, s[6:7]
	s_nop 0
	v_rcp_f32_e32 v134, v112
	v_add_f32_e32 v112, 1.0, v133
	v_mul_f32_e32 v133, 0xbfb8aa3b, v38
	v_exp_f32_e32 v133, v133
	v_mul_f32_e32 v135, 0xbfb8aa3b, v39
	v_exp_f32_e32 v137, v135
	v_rcp_f32_e32 v135, v112
	v_add_f32_e32 v112, 1.0, v133
	v_mul_f32_e32 v133, 0xbfb8aa3b, v32
	v_rcp_f32_e32 v136, v112
	v_add_f32_e32 v112, 1.0, v137
	v_exp_f32_e32 v133, v133
	v_mul_f32_e32 v137, 0xbfb8aa3b, v33
	v_exp_f32_e32 v141, v137
	v_rcp_f32_e32 v137, v112
	v_add_f32_e32 v112, 1.0, v133
	v_mul_f32_e32 v133, 0xbfb8aa3b, v34
	v_rcp_f32_e32 v140, v112
	v_add_f32_e32 v112, 1.0, v141
	v_exp_f32_e32 v133, v133
	v_mul_f32_e32 v141, 0xbfb8aa3b, v35
	v_exp_f32_e32 v143, v141
	v_rcp_f32_e32 v141, v112
	v_add_f32_e32 v112, 1.0, v133
	v_rcp_f32_e32 v142, v112
	v_add_f32_e32 v112, 1.0, v143
	v_rcp_f32_e32 v143, v112
	v_mul_f32_e32 v112, 0xbfb8aa3b, v28
	v_pk_mul_f32 v[134:135], v[36:37], v[134:135]
	v_pk_mul_f32 v[136:137], v[38:39], v[136:137]
	v_pk_mul_f32 v[140:141], v[32:33], v[140:141]
	v_pk_mul_f32 v[142:143], v[34:35], v[142:143]
	v_exp_f32_e32 v112, v112
	v_mul_f32_e32 v133, 0xbfb8aa3b, v29
	v_cvt_pk_bf16_f32 v134, v134, v135
	v_cvt_pk_bf16_f32 v135, v136, v137
	v_cvt_pk_bf16_f32 v136, v140, v141
	v_cvt_pk_bf16_f32 v137, v142, v143
	v_exp_f32_e32 v133, v133
	global_store_dwordx4 v[138:139], v[134:137], off sc1
	v_add_f32_e32 v112, 1.0, v112
	s_nop 0
	v_add_u32_e32 v134, 0xa0, v132
	v_ashrrev_i32_e32 v135, 31, v134
	v_lshlrev_b64 v[134:135], 11, v[134:135]
	v_lshl_add_u64 v[138:139], v[130:131], 0, v[134:135]
	v_rcp_f32_e32 v134, v112
	v_add_f32_e32 v112, 1.0, v133
	v_mul_f32_e32 v133, 0xbfb8aa3b, v30
	v_exp_f32_e32 v133, v133
	v_mul_f32_e32 v135, 0xbfb8aa3b, v31
	v_exp_f32_e32 v137, v135
	v_rcp_f32_e32 v135, v112
	v_add_f32_e32 v112, 1.0, v133
	v_mul_f32_e32 v133, 0xbfb8aa3b, v24
	v_rcp_f32_e32 v136, v112
	v_add_f32_e32 v112, 1.0, v137
	v_exp_f32_e32 v133, v133
	v_mul_f32_e32 v137, 0xbfb8aa3b, v25
	v_exp_f32_e32 v141, v137
	v_rcp_f32_e32 v137, v112
	v_add_f32_e32 v112, 1.0, v133
	v_mul_f32_e32 v133, 0xbfb8aa3b, v26
	v_rcp_f32_e32 v140, v112
	v_add_f32_e32 v112, 1.0, v141
	v_exp_f32_e32 v133, v133
	v_mul_f32_e32 v141, 0xbfb8aa3b, v27
	v_exp_f32_e32 v143, v141
	v_rcp_f32_e32 v141, v112
	v_add_f32_e32 v112, 1.0, v133
	v_rcp_f32_e32 v142, v112
	v_add_f32_e32 v112, 1.0, v143
	v_rcp_f32_e32 v143, v112
	v_mul_f32_e32 v112, 0xbfb8aa3b, v20
	v_exp_f32_e32 v112, v112
	v_mul_f32_e32 v133, 0xbfb8aa3b, v21
	v_exp_f32_e32 v133, v133
	v_pk_mul_f32 v[134:135], v[28:29], v[134:135]
	v_pk_mul_f32 v[136:137], v[30:31], v[136:137]
	v_pk_mul_f32 v[140:141], v[24:25], v[140:141]
	v_pk_mul_f32 v[142:143], v[26:27], v[142:143]
	v_cvt_pk_bf16_f32 v134, v134, v135
	v_cvt_pk_bf16_f32 v135, v136, v137
	v_cvt_pk_bf16_f32 v136, v140, v141
	v_cvt_pk_bf16_f32 v137, v142, v143
	v_lshl_add_u64 v[140:141], v[138:139], 0, s[4:5]
	v_add_f32_e32 v112, 1.0, v112
	global_store_dwordx4 v[140:141], v[134:137], off sc1
	v_add_u32_e32 v132, 0xb0, v132
	v_lshl_add_u64 v[138:139], v[138:139], 0, s[6:7]
	v_rcp_f32_e32 v134, v112
	v_add_f32_e32 v112, 1.0, v133
	v_mul_f32_e32 v133, 0xbfb8aa3b, v22
	v_exp_f32_e32 v133, v133
	v_mul_f32_e32 v135, 0xbfb8aa3b, v23
	v_exp_f32_e32 v137, v135
	v_rcp_f32_e32 v135, v112
	v_add_f32_e32 v112, 1.0, v133
	v_mul_f32_e32 v133, 0xbfb8aa3b, v16
	v_rcp_f32_e32 v136, v112
	v_add_f32_e32 v112, 1.0, v137
	v_exp_f32_e32 v133, v133
	v_mul_f32_e32 v137, 0xbfb8aa3b, v17
	v_exp_f32_e32 v141, v137
	v_rcp_f32_e32 v137, v112
	v_add_f32_e32 v112, 1.0, v133
	v_mul_f32_e32 v133, 0xbfb8aa3b, v18
	v_rcp_f32_e32 v140, v112
	v_add_f32_e32 v112, 1.0, v141
	v_exp_f32_e32 v133, v133
	v_mul_f32_e32 v141, 0xbfb8aa3b, v19
	v_exp_f32_e32 v143, v141
	v_rcp_f32_e32 v141, v112
	v_add_f32_e32 v112, 1.0, v133
	v_rcp_f32_e32 v142, v112
	v_add_f32_e32 v112, 1.0, v143
	v_rcp_f32_e32 v143, v112
	v_pk_mul_f32 v[134:135], v[20:21], v[134:135]
	v_pk_mul_f32 v[136:137], v[22:23], v[136:137]
	v_pk_mul_f32 v[140:141], v[16:17], v[140:141]
	v_pk_mul_f32 v[142:143], v[18:19], v[142:143]
	v_cvt_pk_bf16_f32 v134, v134, v135
	v_cvt_pk_bf16_f32 v135, v136, v137
	v_cvt_pk_bf16_f32 v136, v140, v141
	v_cvt_pk_bf16_f32 v137, v142, v143
	v_ashrrev_i32_e32 v133, 31, v132
	v_mul_f32_e32 v112, 0xbfb8aa3b, v12
	global_store_dwordx4 v[138:139], v[134:137], off sc1
	v_lshlrev_b64 v[132:133], 11, v[132:133]
	v_exp_f32_e32 v112, v112
	v_mul_f32_e32 v134, 0xbfb8aa3b, v13
	v_exp_f32_e32 v136, v134
	v_lshl_add_u64 v[134:135], v[130:131], 0, v[132:133]
	v_mul_f32_e32 v131, 0xbfb8aa3b, v14
	v_exp_f32_e32 v132, v131
	v_mul_f32_e32 v131, 0xbfb8aa3b, v15
	v_exp_f32_e32 v133, v131
	v_add_f32_e32 v112, 1.0, v112
	v_rcp_f32_e32 v130, v112
	v_add_f32_e32 v112, 1.0, v136
	v_rcp_f32_e32 v131, v112
	v_add_f32_e32 v112, 1.0, v132
	v_rcp_f32_e32 v132, v112
	v_add_f32_e32 v112, 1.0, v133
	v_mul_f32_e32 v133, 0xbfb8aa3b, v4
	v_exp_f32_e32 v136, v133
	v_mul_f32_e32 v133, 0xbfb8aa3b, v5
	v_exp_f32_e32 v137, v133
	v_rcp_f32_e32 v133, v112
	v_add_f32_e32 v112, 1.0, v136
	v_rcp_f32_e32 v136, v112
	v_add_f32_e32 v112, 1.0, v137
	v_mul_f32_e32 v137, 0xbfb8aa3b, v6
	v_exp_f32_e32 v138, v137
	v_mul_f32_e32 v137, 0xbfb8aa3b, v7
	v_exp_f32_e32 v139, v137
	v_rcp_f32_e32 v137, v112
	v_add_f32_e32 v112, 1.0, v138
	v_rcp_f32_e32 v138, v112
	v_add_f32_e32 v112, 1.0, v139
	v_rcp_f32_e32 v139, v112
	v_pk_mul_f32 v[130:131], v[12:13], v[130:131]
	v_pk_mul_f32 v[132:133], v[14:15], v[132:133]
	v_pk_mul_f32 v[136:137], v[4:5], v[136:137]
	v_pk_mul_f32 v[138:139], v[6:7], v[138:139]
	v_mul_f32_e32 v112, 0xbfb8aa3b, v8
	v_cvt_pk_bf16_f32 v130, v130, v131
	v_cvt_pk_bf16_f32 v131, v132, v133
	v_cvt_pk_bf16_f32 v132, v136, v137
	v_cvt_pk_bf16_f32 v133, v138, v139
	v_lshl_add_u64 v[136:137], v[134:135], 0, s[4:5]
	v_exp_f32_e32 v112, v112
	v_mul_f32_e32 v138, 0xbfb8aa3b, v9
	v_exp_f32_e32 v138, v138
	global_store_dwordx4 v[136:137], v[130:133], off sc1
	v_add_f32_e32 v112, 1.0, v112
	v_lshl_add_u64 v[134:135], v[134:135], 0, s[6:7]
	v_mul_f32_e32 v131, 0xbfb8aa3b, v10
	v_exp_f32_e32 v132, v131
	v_mul_f32_e32 v131, 0xbfb8aa3b, v11
	v_exp_f32_e32 v133, v131
	v_rcp_f32_e32 v130, v112
	v_add_f32_e32 v112, 1.0, v138
	v_rcp_f32_e32 v131, v112
	v_add_f32_e32 v112, 1.0, v132
	v_rcp_f32_e32 v132, v112
	v_add_f32_e32 v112, 1.0, v133
	v_mul_f32_e32 v133, 0xbfb8aa3b, v0
	v_exp_f32_e32 v136, v133
	v_mul_f32_e32 v133, 0xbfb8aa3b, v1
	v_exp_f32_e32 v137, v133
	v_rcp_f32_e32 v133, v112
	v_add_f32_e32 v112, 1.0, v136
	v_rcp_f32_e32 v136, v112
	v_add_f32_e32 v112, 1.0, v137
	v_mul_f32_e32 v137, 0xbfb8aa3b, v2
	v_exp_f32_e32 v138, v137
	v_mul_f32_e32 v137, 0xbfb8aa3b, v3
	v_exp_f32_e32 v139, v137
	v_rcp_f32_e32 v137, v112
	v_add_f32_e32 v112, 1.0, v138
	v_rcp_f32_e32 v138, v112
	v_add_f32_e32 v112, 1.0, v139
	v_rcp_f32_e32 v139, v112
	v_pk_mul_f32 v[130:131], v[8:9], v[130:131]
	v_pk_mul_f32 v[132:133], v[10:11], v[132:133]
	v_pk_mul_f32 v[136:137], v[0:1], v[136:137]
	v_pk_mul_f32 v[138:139], v[2:3], v[138:139]
	v_cvt_pk_bf16_f32 v130, v130, v131
	v_cvt_pk_bf16_f32 v131, v132, v133
	v_cvt_pk_bf16_f32 v132, v136, v137
	v_cvt_pk_bf16_f32 v133, v138, v139
	global_store_dwordx4 v[134:135], v[130:133], off sc1
